# v5 + grid-barrier poll interval s_sleep 2 -> s_sleep 1 (23 poll loops)
# speedup vs baseline: 1.0122x; 1.0045x over previous
; DI int lane_id() { int l; asm volatile("v_mbcnt_lo_u32_b32 %0, -1, 0\n\tv_mbcnt_hi_u32_b32 %0, -1, %0" : "=v"(l)); return l; }
; DI void gbar(unsigned* ctr, unsigned& epoch, int wv) {
;     asm volatile("s_waitcnt vmcnt(0) lgkmcnt(0)" ::: "memory");
;     __syncthreads();
;     ++epoch;
;     unsigned target = epoch * gridDim.x; asm volatile("" : "+s"(target));
;     if (wv == 0 && lane_id() == 0) {
;         __builtin_amdgcn_fence(__ATOMIC_RELEASE, "agent");
;         asm volatile("s_waitcnt vmcnt(0)" ::: "memory");
;         __hip_atomic_fetch_add(ctr, 1u, __ATOMIC_RELAXED, __HIP_MEMORY_SCOPE_AGENT);
;         while (__hip_atomic_load(ctr, __ATOMIC_RELAXED, __HIP_MEMORY_SCOPE_AGENT) < target) __builtin_amdgcn_s_sleep(2);
;         __builtin_amdgcn_fence(__ATOMIC_ACQUIRE, "agent");
;         asm volatile("s_waitcnt vmcnt(0)" ::: "memory");
;     }
;     __syncthreads();
; }
.LBB1_539:
	s_sleep 1
	global_load_dword v1, v0, s[18:19] offset:256 sc1
	s_waitcnt vmcnt(0)
	v_cmp_gt_u32_e32 vcc, s8, v1
	s_cbranch_vccnz .LBB1_539

; DI int lane_id() { int l; asm volatile("v_mbcnt_lo_u32_b32 %0, -1, 0\n\tv_mbcnt_hi_u32_b32 %0, -1, %0" : "=v"(l)); return l; }
; DI void gbar(unsigned* ctr, unsigned& epoch, int wv) {
;     asm volatile("s_waitcnt vmcnt(0) lgkmcnt(0)" ::: "memory");
;     __syncthreads();
;     ++epoch;
;     unsigned target = epoch * gridDim.x; asm volatile("" : "+s"(target));
;     if (wv == 0 && lane_id() == 0) {
;         __builtin_amdgcn_fence(__ATOMIC_RELEASE, "agent");
;         asm volatile("s_waitcnt vmcnt(0)" ::: "memory");
;         __hip_atomic_fetch_add(ctr, 1u, __ATOMIC_RELAXED, __HIP_MEMORY_SCOPE_AGENT);
;         while (__hip_atomic_load(ctr, __ATOMIC_RELAXED, __HIP_MEMORY_SCOPE_AGENT) < target) __builtin_amdgcn_s_sleep(2);
;         __builtin_amdgcn_fence(__ATOMIC_ACQUIRE, "agent");
;         asm volatile("s_waitcnt vmcnt(0)" ::: "memory");
;     }
;     __syncthreads();
; }
.LBB1_581:
	s_sleep 1
	global_load_dword v1, v0, s[18:19] offset:256 sc1
	s_waitcnt vmcnt(0)
	v_cmp_gt_u32_e32 vcc, s6, v1
	s_cbranch_vccnz .LBB1_581

; DI int lane_id() { int l; asm volatile("v_mbcnt_lo_u32_b32 %0, -1, 0\n\tv_mbcnt_hi_u32_b32 %0, -1, %0" : "=v"(l)); return l; }
; DI void gbar(unsigned* ctr, unsigned& epoch, int wv) {
;     asm volatile("s_waitcnt vmcnt(0) lgkmcnt(0)" ::: "memory");
;     __syncthreads();
;     ++epoch;
;     unsigned target = epoch * gridDim.x; asm volatile("" : "+s"(target));
;     if (wv == 0 && lane_id() == 0) {
;         __builtin_amdgcn_fence(__ATOMIC_RELEASE, "agent");
;         asm volatile("s_waitcnt vmcnt(0)" ::: "memory");
;         __hip_atomic_fetch_add(ctr, 1u, __ATOMIC_RELAXED, __HIP_MEMORY_SCOPE_AGENT);
;         while (__hip_atomic_load(ctr, __ATOMIC_RELAXED, __HIP_MEMORY_SCOPE_AGENT) < target) __builtin_amdgcn_s_sleep(2);
;         __builtin_amdgcn_fence(__ATOMIC_ACQUIRE, "agent");
;         asm volatile("s_waitcnt vmcnt(0)" ::: "memory");
;     }
;     __syncthreads();
; }
.LBB1_762:
	s_sleep 1
	global_load_dword v0, v1, s[18:19] offset:256 sc1
	s_waitcnt vmcnt(0)
	v_cmp_gt_u32_e32 vcc, s39, v0
	s_cbranch_vccnz .LBB1_762

; DI int lane_id() { int l; asm volatile("v_mbcnt_lo_u32_b32 %0, -1, 0\n\tv_mbcnt_hi_u32_b32 %0, -1, %0" : "=v"(l)); return l; }
; DI void gbar(unsigned* ctr, unsigned& epoch, int wv) {
;     asm volatile("s_waitcnt vmcnt(0) lgkmcnt(0)" ::: "memory");
;     __syncthreads();
;     ++epoch;
;     unsigned target = epoch * gridDim.x; asm volatile("" : "+s"(target));
;     if (wv == 0 && lane_id() == 0) {
;         __builtin_amdgcn_fence(__ATOMIC_RELEASE, "agent");
;         asm volatile("s_waitcnt vmcnt(0)" ::: "memory");
;         __hip_atomic_fetch_add(ctr, 1u, __ATOMIC_RELAXED, __HIP_MEMORY_SCOPE_AGENT);
;         while (__hip_atomic_load(ctr, __ATOMIC_RELAXED, __HIP_MEMORY_SCOPE_AGENT) < target) __builtin_amdgcn_s_sleep(2);
;         __builtin_amdgcn_fence(__ATOMIC_ACQUIRE, "agent");
;         asm volatile("s_waitcnt vmcnt(0)" ::: "memory");
;     }
;     __syncthreads();
; }
.LBB1_862:
	s_sleep 1
	global_load_dword v0, v1, s[18:19] offset:256 sc1
	s_waitcnt vmcnt(0)
	v_cmp_gt_u32_e32 vcc, s24, v0
	s_cbranch_vccnz .LBB1_862

; DI int lane_id() { int l; asm volatile("v_mbcnt_lo_u32_b32 %0, -1, 0\n\tv_mbcnt_hi_u32_b32 %0, -1, %0" : "=v"(l)); return l; }
; DI void gbar(unsigned* ctr, unsigned& epoch, int wv) {
;     asm volatile("s_waitcnt vmcnt(0) lgkmcnt(0)" ::: "memory");
;     __syncthreads();
;     ++epoch;
;     unsigned target = epoch * gridDim.x; asm volatile("" : "+s"(target));
;     if (wv == 0 && lane_id() == 0) {
;         __builtin_amdgcn_fence(__ATOMIC_RELEASE, "agent");
;         asm volatile("s_waitcnt vmcnt(0)" ::: "memory");
;         __hip_atomic_fetch_add(ctr, 1u, __ATOMIC_RELAXED, __HIP_MEMORY_SCOPE_AGENT);
;         while (__hip_atomic_load(ctr, __ATOMIC_RELAXED, __HIP_MEMORY_SCOPE_AGENT) < target) __builtin_amdgcn_s_sleep(2);
;         __builtin_amdgcn_fence(__ATOMIC_ACQUIRE, "agent");
;         asm volatile("s_waitcnt vmcnt(0)" ::: "memory");
;     }
;     __syncthreads();
; }
.LBB1_900:
	s_sleep 1
	global_load_dword v0, v1, s[18:19] offset:256 sc1
	s_waitcnt vmcnt(0)
	v_cmp_gt_u32_e32 vcc, s25, v0
	s_cbranch_vccnz .LBB1_900

; DI int lane_id() { int l; asm volatile("v_mbcnt_lo_u32_b32 %0, -1, 0\n\tv_mbcnt_hi_u32_b32 %0, -1, %0" : "=v"(l)); return l; }
; DI void gbar(unsigned* ctr, unsigned& epoch, int wv) {
;     asm volatile("s_waitcnt vmcnt(0) lgkmcnt(0)" ::: "memory");
;     __syncthreads();
;     ++epoch;
;     unsigned target = epoch * gridDim.x; asm volatile("" : "+s"(target));
;     if (wv == 0 && lane_id() == 0) {
;         __builtin_amdgcn_fence(__ATOMIC_RELEASE, "agent");
;         asm volatile("s_waitcnt vmcnt(0)" ::: "memory");
;         __hip_atomic_fetch_add(ctr, 1u, __ATOMIC_RELAXED, __HIP_MEMORY_SCOPE_AGENT);
;         while (__hip_atomic_load(ctr, __ATOMIC_RELAXED, __HIP_MEMORY_SCOPE_AGENT) < target) __builtin_amdgcn_s_sleep(2);
;         __builtin_amdgcn_fence(__ATOMIC_ACQUIRE, "agent");
;         asm volatile("s_waitcnt vmcnt(0)" ::: "memory");
;     }
;     __syncthreads();
; }
.LBB1_964:
	s_sleep 1
	global_load_dword v0, v1, s[18:19] offset:256 sc1
	s_waitcnt vmcnt(0)
	v_cmp_gt_u32_e32 vcc, s13, v0
	s_cbranch_vccnz .LBB1_964

; DI int lane_id() { int l; asm volatile("v_mbcnt_lo_u32_b32 %0, -1, 0\n\tv_mbcnt_hi_u32_b32 %0, -1, %0" : "=v"(l)); return l; }
; DI void gbar(unsigned* ctr, unsigned& epoch, int wv) {
;     asm volatile("s_waitcnt vmcnt(0) lgkmcnt(0)" ::: "memory");
;     __syncthreads();
;     ++epoch;
;     unsigned target = epoch * gridDim.x; asm volatile("" : "+s"(target));
;     if (wv == 0 && lane_id() == 0) {
;         __builtin_amdgcn_fence(__ATOMIC_RELEASE, "agent");
;         asm volatile("s_waitcnt vmcnt(0)" ::: "memory");
;         __hip_atomic_fetch_add(ctr, 1u, __ATOMIC_RELAXED, __HIP_MEMORY_SCOPE_AGENT);
;         while (__hip_atomic_load(ctr, __ATOMIC_RELAXED, __HIP_MEMORY_SCOPE_AGENT) < target) __builtin_amdgcn_s_sleep(2);
;         __builtin_amdgcn_fence(__ATOMIC_ACQUIRE, "agent");
;         asm volatile("s_waitcnt vmcnt(0)" ::: "memory");
;     }
;     __syncthreads();
; }
.LBB1_1022:
	s_sleep 1
	global_load_dword v0, v1, s[18:19] offset:256 sc1
	s_waitcnt vmcnt(0)
	v_cmp_gt_u32_e32 vcc, s12, v0
	s_cbranch_vccnz .LBB1_1022

; DI int lane_id() { int l; asm volatile("v_mbcnt_lo_u32_b32 %0, -1, 0\n\tv_mbcnt_hi_u32_b32 %0, -1, %0" : "=v"(l)); return l; }
; DI void gbar_grp(unsigned* ctr0, unsigned& gepoch, int wv) {
;     asm volatile("s_waitcnt vmcnt(0) lgkmcnt(0)" ::: "memory");
;     __syncthreads();
;     ++gepoch;
;     unsigned target = gepoch * (gridDim.x >> 3); asm volatile("" : "+s"(target));
;     if (wv == 0 && lane_id() == 0) {
;         unsigned* ctr = ctr0 + 64 * (blockIdx.x & 7);
;         __builtin_amdgcn_fence(__ATOMIC_RELEASE, "agent");
;         asm volatile("s_waitcnt vmcnt(0)" ::: "memory");
;         __hip_atomic_fetch_add(ctr, 1u, __ATOMIC_RELAXED, __HIP_MEMORY_SCOPE_AGENT);
;         while (__hip_atomic_load(ctr, __ATOMIC_RELAXED, __HIP_MEMORY_SCOPE_AGENT) < target) __builtin_amdgcn_s_sleep(2);
;         __builtin_amdgcn_fence(__ATOMIC_ACQUIRE, "agent");
;         asm volatile("s_waitcnt vmcnt(0)" ::: "memory");
;     }
;     __syncthreads();
; }
.LBB1_1034:
	s_sleep 1
	global_load_dword v0, v1, s[30:31] offset:1280 sc1
	s_waitcnt vmcnt(0)
	v_cmp_gt_u32_e32 vcc, s11, v0
	s_cbranch_vccnz .LBB1_1034

; DI int lane_id() { int l; asm volatile("v_mbcnt_lo_u32_b32 %0, -1, 0\n\tv_mbcnt_hi_u32_b32 %0, -1, %0" : "=v"(l)); return l; }
; DI void gbar(unsigned* ctr, unsigned& epoch, int wv) {
;     asm volatile("s_waitcnt vmcnt(0) lgkmcnt(0)" ::: "memory");
;     __syncthreads();
;     ++epoch;
;     unsigned target = epoch * gridDim.x; asm volatile("" : "+s"(target));
;     if (wv == 0 && lane_id() == 0) {
;         __builtin_amdgcn_fence(__ATOMIC_RELEASE, "agent");
;         asm volatile("s_waitcnt vmcnt(0)" ::: "memory");
;         __hip_atomic_fetch_add(ctr, 1u, __ATOMIC_RELAXED, __HIP_MEMORY_SCOPE_AGENT);
;         while (__hip_atomic_load(ctr, __ATOMIC_RELAXED, __HIP_MEMORY_SCOPE_AGENT) < target) __builtin_amdgcn_s_sleep(2);
;         __builtin_amdgcn_fence(__ATOMIC_ACQUIRE, "agent");
;         asm volatile("s_waitcnt vmcnt(0)" ::: "memory");
;     }
;     __syncthreads();
; }
.LBB1_1146:
	s_sleep 1
	global_load_dword v0, v1, s[18:19] offset:256 sc1
	s_waitcnt vmcnt(0)
	v_cmp_gt_u32_e32 vcc, s9, v0
	s_cbranch_vccnz .LBB1_1146

; DI int lane_id() { int l; asm volatile("v_mbcnt_lo_u32_b32 %0, -1, 0\n\tv_mbcnt_hi_u32_b32 %0, -1, %0" : "=v"(l)); return l; }
; DI void gbar_grp(unsigned* ctr0, unsigned& gepoch, int wv) {
;     asm volatile("s_waitcnt vmcnt(0) lgkmcnt(0)" ::: "memory");
;     __syncthreads();
;     ++gepoch;
;     unsigned target = gepoch * (gridDim.x >> 3); asm volatile("" : "+s"(target));
;     if (wv == 0 && lane_id() == 0) {
;         unsigned* ctr = ctr0 + 64 * (blockIdx.x & 7);
;         __builtin_amdgcn_fence(__ATOMIC_RELEASE, "agent");
;         asm volatile("s_waitcnt vmcnt(0)" ::: "memory");
;         __hip_atomic_fetch_add(ctr, 1u, __ATOMIC_RELAXED, __HIP_MEMORY_SCOPE_AGENT);
;         while (__hip_atomic_load(ctr, __ATOMIC_RELAXED, __HIP_MEMORY_SCOPE_AGENT) < target) __builtin_amdgcn_s_sleep(2);
;         __builtin_amdgcn_fence(__ATOMIC_ACQUIRE, "agent");
;         asm volatile("s_waitcnt vmcnt(0)" ::: "memory");
;     }
;     __syncthreads();
; }
.LBB1_1155:
	s_sleep 1
	global_load_dword v0, v1, s[30:31] offset:1280 sc1
	s_waitcnt vmcnt(0)
	v_cmp_gt_u32_e32 vcc, s8, v0
	s_cbranch_vccnz .LBB1_1155

; DI int lane_id() { int l; asm volatile("v_mbcnt_lo_u32_b32 %0, -1, 0\n\tv_mbcnt_hi_u32_b32 %0, -1, %0" : "=v"(l)); return l; }
; DI void gbar(unsigned* ctr, unsigned& epoch, int wv) {
;     asm volatile("s_waitcnt vmcnt(0) lgkmcnt(0)" ::: "memory");
;     __syncthreads();
;     ++epoch;
;     unsigned target = epoch * gridDim.x; asm volatile("" : "+s"(target));
;     if (wv == 0 && lane_id() == 0) {
;         __builtin_amdgcn_fence(__ATOMIC_RELEASE, "agent");
;         asm volatile("s_waitcnt vmcnt(0)" ::: "memory");
;         __hip_atomic_fetch_add(ctr, 1u, __ATOMIC_RELAXED, __HIP_MEMORY_SCOPE_AGENT);
;         while (__hip_atomic_load(ctr, __ATOMIC_RELAXED, __HIP_MEMORY_SCOPE_AGENT) < target) __builtin_amdgcn_s_sleep(2);
;         __builtin_amdgcn_fence(__ATOMIC_ACQUIRE, "agent");
;         asm volatile("s_waitcnt vmcnt(0)" ::: "memory");
;     }
;     __syncthreads();
; }
.LBB1_1249:
	s_sleep 1
	global_load_dword v0, v1, s[18:19] offset:256 sc1
	s_waitcnt vmcnt(0)
	v_cmp_gt_u32_e32 vcc, s11, v0
	s_cbranch_vccnz .LBB1_1249

; DI int lane_id() { int l; asm volatile("v_mbcnt_lo_u32_b32 %0, -1, 0\n\tv_mbcnt_hi_u32_b32 %0, -1, %0" : "=v"(l)); return l; }
; DI void gbar_grp(unsigned* ctr0, unsigned& gepoch, int wv) {
;     asm volatile("s_waitcnt vmcnt(0) lgkmcnt(0)" ::: "memory");
;     __syncthreads();
;     ++gepoch;
;     unsigned target = gepoch * (gridDim.x >> 3); asm volatile("" : "+s"(target));
;     if (wv == 0 && lane_id() == 0) {
;         unsigned* ctr = ctr0 + 64 * (blockIdx.x & 7);
;         __builtin_amdgcn_fence(__ATOMIC_RELEASE, "agent");
;         asm volatile("s_waitcnt vmcnt(0)" ::: "memory");
;         __hip_atomic_fetch_add(ctr, 1u, __ATOMIC_RELAXED, __HIP_MEMORY_SCOPE_AGENT);
;         while (__hip_atomic_load(ctr, __ATOMIC_RELAXED, __HIP_MEMORY_SCOPE_AGENT) < target) __builtin_amdgcn_s_sleep(2);
;         __builtin_amdgcn_fence(__ATOMIC_ACQUIRE, "agent");
;         asm volatile("s_waitcnt vmcnt(0)" ::: "memory");
;     }
;     __syncthreads();
; }
.LBB1_1360:
	s_sleep 1
	global_load_dword v0, v1, s[30:31] offset:1280 sc1
	s_waitcnt vmcnt(0)
	v_cmp_gt_u32_e32 vcc, s13, v0
	s_cbranch_vccnz .LBB1_1360

; DI int lane_id() { int l; asm volatile("v_mbcnt_lo_u32_b32 %0, -1, 0\n\tv_mbcnt_hi_u32_b32 %0, -1, %0" : "=v"(l)); return l; }
; DI void gbar_grp(unsigned* ctr0, unsigned& gepoch, int wv) {
;     asm volatile("s_waitcnt vmcnt(0) lgkmcnt(0)" ::: "memory");
;     __syncthreads();
;     ++gepoch;
;     unsigned target = gepoch * (gridDim.x >> 3); asm volatile("" : "+s"(target));
;     if (wv == 0 && lane_id() == 0) {
;         unsigned* ctr = ctr0 + 64 * (blockIdx.x & 7);
;         __builtin_amdgcn_fence(__ATOMIC_RELEASE, "agent");
;         asm volatile("s_waitcnt vmcnt(0)" ::: "memory");
;         __hip_atomic_fetch_add(ctr, 1u, __ATOMIC_RELAXED, __HIP_MEMORY_SCOPE_AGENT);
;         while (__hip_atomic_load(ctr, __ATOMIC_RELAXED, __HIP_MEMORY_SCOPE_AGENT) < target) __builtin_amdgcn_s_sleep(2);
;         __builtin_amdgcn_fence(__ATOMIC_ACQUIRE, "agent");
;         asm volatile("s_waitcnt vmcnt(0)" ::: "memory");
;     }
;     __syncthreads();
; }
.LBB1_1445:
	s_sleep 1
	global_load_dword v0, v1, s[30:31] offset:1280 sc1
	s_waitcnt vmcnt(0)
	v_cmp_gt_u32_e32 vcc, s10, v0
	s_cbranch_vccnz .LBB1_1445
